# v33 + GATE epilogue first block: o-tile and row-scale loads hoisted next to the stats loads
# baseline (speedup 1.0000x reference)
; DI void gemm_epilogue(const GemmDesc& g, f32x4 (&acc)[2][2][4][2], int brow, int bcol, int wr, int wc, int fr, int fq) {
;     ...
;     const int N = g.N, dvm = (1 << g.dvshift) - 1;
; #pragma unroll
;     for (int bj = 0; bj < 2; ++bj) {
;       const int col = colb + bj * HALF;
;       f32x4 g0 = {1.f, 1.f, 1.f, 1.f}, g1 = g0;
;       if (g.c0) { g0 = gld<f32x4>(g.c0 + (col & dvm)); g1 = gld<f32x4>(g.c0 + (col & dvm) + 4); }
;       const int head = col >> g.dvshift;
; #pragma unroll
;       for (int ai = 0; ai < 2; ++ai)
; #pragma unroll
;         for (int m = 0; m < 4; ++m) {
;           const int row = rowb + ai * HALF + m * 16;
;           float rs;
;           { const float* sp = g.f0 + (size_t)row * 32 + head * 8;
;             const f32x4 s0 = gld<f32x4>(sp); float ssum = (s0[0] + s0[1]) + (s0[2] + s0[3]);
;             if (g.dvshift == 9) { const f32x4 s1 = gld<f32x4>(sp + 4); ssum += (s1[0] + s1[1]) + (s1[2] + s1[3]); }
;             rs = rsqrtf(ssum * (g.dvshift == 9 ? (1.0f / 512.0f) : (1.0f / 256.0f)) + EPS); }
;           bf16_t* op = g.o0 + (size_t)row * N + col;
;           const u32x4 ow = gld<u32x4>(op);
;           const float ru = gld<float>(g.rowscale + row);
;           const f32x4 v0 = acc[ai][bj][m][0] * ru, v1 = acc[ai][bj][m][1] * ru;
.LBB0_219:
	v_readlane_b32 s26, v255, 29
	v_ashrrev_i32_e32 v167, 31, v166
	v_readlane_b32 vcc_lo, v255, 27
	v_ashrrev_i32_e32 v136, s26, v164
	v_lshlrev_b32_e32 v180, 3, v136
	v_lshlrev_b64 v[136:137], 7, v[166:167]
	v_ashrrev_i32_e32 v181, 31, v180
	v_lshl_add_u64 v[182:183], s[66:67], 0, v[136:137]
	v_lshl_add_u64 v[136:137], v[180:181], 2, v[182:183]
	global_load_dwordx4 v[138:141], v[136:137], off
	global_load_dwordx4 v[232:235], v[136:137], off offset:16
	v_mov_b32_e32 v248, v164
	v_ashrrev_i32_e32 v249, 31, v164
	v_mad_u64_u32 v[238:239], s[100:101], v166, s70, 0
	v_mov_b32_e32 v240, v239
	v_mad_u64_u32 v[240:241], s[100:101], v167, s70, v[240:241]
	v_mov_b32_e32 v239, v240
	v_lshl_add_u64 v[238:239], v[238:239], 1, s[64:65]
	v_lshl_add_u64 v[236:237], v[248:249], 1, v[238:239]
	global_load_dwordx4 v[242:245], v[236:237], off
	v_lshl_add_u64 v[248:249], v[166:167], 2, s[22:23]
	global_load_dword v246, v[248:249], off
	v_readlane_b32 vcc_hi, v255, 28
	s_mov_b32 s26, 0x3b800000
	s_mov_b32 s27, 0x3b800000
	v_cndmask_b32_e64 v142, 0, 1, vcc
	v_cmp_ne_u32_e64 s[44:45], 1, v142
	s_andn2_b64 vcc, exec, vcc
	s_waitcnt vmcnt(0)
	v_mov_b32_e32 v142, v139
	v_mov_b32_e32 v143, v140
	v_mov_b32_e32 v139, v141
	v_pk_add_f32 v[138:139], v[142:143], v[138:139]
	s_nop 0
	v_pk_add_f32 v[138:139], v[138:139], v[138:139] op_sel:[0,1] op_sel_hi:[1,0]
	s_cbranch_vccnz .LBB0_221
	v_mov_b64_e32 v[140:141], v[232:233]
	v_mov_b64_e32 v[142:143], v[234:235]
	s_mov_b32 s27, 0x3b000000
	v_mov_b32_e32 v136, v141
	v_mov_b32_e32 v137, v142
	v_mov_b32_e32 v141, v143
	v_pk_add_f32 v[136:137], v[136:137], v[140:141]
	s_nop 0
	v_add_f32_e32 v136, v136, v137
	v_add_f32_e32 v138, v138, v136
.LBB0_221:
	v_fma_f32 v136, s27, v138, v204
	v_cmp_gt_f32_e32 vcc, s33, v136
	v_mul_f32_e32 v137, 0x4b800000, v136
	v_ashrrev_i32_e32 v165, 31, v164
	v_cndmask_b32_e32 v136, v136, v137, vcc
	v_rsq_f32_e32 v136, v136
	v_lshl_add_u64 v[140:141], v[166:167], 2, s[22:23]
	v_mov_b32_e32 v168, v246
	v_mul_f32_e32 v137, 0x45800000, v136
	v_cndmask_b32_e32 v148, v136, v137, vcc
	v_mad_u64_u32 v[136:137], vcc, v166, s70, 0
	v_mov_b32_e32 v138, v137
	v_mad_u64_u32 v[138:139], vcc, v167, s70, v[138:139]
	v_mov_b32_e32 v137, v138
	v_lshl_add_u64 v[136:137], v[136:137], 1, s[64:65]
	v_lshl_add_u64 v[142:143], v[164:165], 1, v[136:137]
	v_mov_b64_e32 v[136:137], v[242:243]
	v_mov_b64_e32 v[138:139], v[244:245]
	v_pk_mul_f32 v[172:173], v[124:125], v[168:169] op_sel_hi:[1,0]
	v_lshlrev_b32_e32 v170, 16, v136
	v_and_b32_e32 v171, 0xffff0000, v136
	v_mul_f32_e32 v136, 0xbfb8aa3b, v172
	v_exp_f32_e32 v174, v136
	v_mul_f32_e32 v136, 0xbfb8aa3b, v173
	v_exp_f32_e32 v175, v136
	v_pk_mul_f32 v[170:171], v[148:149], v[170:171] op_sel_hi:[0,1]
	v_pk_mul_f32 v[170:171], v[132:133], v[170:171]
	s_nop 0
	v_pk_mul_f32 v[170:171], v[172:173], v[170:171]
	v_pk_add_f32 v[172:173], v[174:175], 1.0 op_sel_hi:[1,0]
	s_nop 0
	v_div_scale_f32 v136, vcc, v173, v173, 1.0
	v_rcp_f32_e32 v167, v136
	s_nop 0
	v_fma_f32 v169, -v136, v167, 1.0
	v_fmac_f32_e32 v167, v169, v167
	v_div_scale_f32 v169, vcc, 1.0, v173, 1.0
	v_mul_f32_e32 v174, v169, v167
	v_fma_f32 v175, -v136, v174, v169
	v_fmac_f32_e32 v174, v175, v167
	v_fma_f32 v136, -v136, v174, v169
	v_div_fmas_f32 v136, v136, v167, v174
	v_div_fixup_f32 v173, v136, v173, 1.0
	v_div_scale_f32 v136, vcc, v172, v172, 1.0
	v_rcp_f32_e32 v167, v136
	s_nop 0
	v_fma_f32 v169, -v136, v167, 1.0
	v_fmac_f32_e32 v167, v169, v167
	v_div_scale_f32 v169, vcc, 1.0, v172, 1.0
	v_mul_f32_e32 v174, v169, v167
	v_fma_f32 v175, -v136, v174, v169
	v_fmac_f32_e32 v174, v175, v167
	v_fma_f32 v136, -v136, v174, v169
	v_div_fmas_f32 v136, v136, v167, v174
	v_pk_mul_f32 v[174:175], v[120:121], v[168:169] op_sel_hi:[1,0]
	v_div_fixup_f32 v172, v136, v172, 1.0
	v_mul_f32_e32 v136, 0xbfb8aa3b, v174
	v_exp_f32_e32 v176, v136
	v_mul_f32_e32 v136, 0xbfb8aa3b, v175
	v_exp_f32_e32 v177, v136
	v_pk_mul_f32 v[170:171], v[172:173], v[170:171]
	v_lshlrev_b32_e32 v172, 16, v138
	v_and_b32_e32 v173, 0xffff0000, v138
	v_pk_mul_f32 v[172:173], v[148:149], v[172:173] op_sel_hi:[0,1]
	v_pk_mul_f32 v[172:173], v[128:129], v[172:173]
	s_nop 0
	v_pk_mul_f32 v[172:173], v[174:175], v[172:173]
	v_pk_add_f32 v[174:175], v[176:177], 1.0 op_sel_hi:[1,0]
	s_nop 0
	v_div_scale_f32 v136, vcc, v175, v175, 1.0
	v_rcp_f32_e32 v138, v136
	s_nop 0
	v_fma_f32 v167, -v136, v138, 1.0
	v_fmac_f32_e32 v138, v167, v138
	v_div_scale_f32 v167, vcc, 1.0, v175, 1.0
	v_mul_f32_e32 v169, v167, v138
	v_fma_f32 v176, -v136, v169, v167
	v_fmac_f32_e32 v169, v176, v138
	v_fma_f32 v136, -v136, v169, v167
	v_div_fmas_f32 v136, v136, v138, v169
	v_div_fixup_f32 v175, v136, v175, 1.0
; DI unsigned pk(float lo, float hi) { f32x2 v = {lo, hi}; bf2_t b = __builtin_convertvector(v, bf2_t); return __builtin_bit_cast(unsigned, b); }
; DI float bflo(unsigned w) { return __uint_as_float(w << 16); }
; DI float bfhi(unsigned w) { return __uint_as_float(w & 0xffff0000u); }
; DI float sigmoidf_(float x) { return 1.0f / (1.0f + __expf(-x)); }
; DI void gemm_epilogue(const GemmDesc& g, f32x4 (&acc)[2][2][4][2], int brow, int bcol, int wr, int wc, int fr, int fq) {
;     ...
;           const int row = rowb + ai * HALF + m * 16;
;           float rs;
;           { const float* sp = g.f0 + (size_t)row * 32 + head * 8;
;             const f32x4 s0 = gld<f32x4>(sp); float ssum = (s0[0] + s0[1]) + (s0[2] + s0[3]);
;             if (g.dvshift == 9) { const f32x4 s1 = gld<f32x4>(sp + 4); ssum += (s1[0] + s1[1]) + (s1[2] + s1[3]); }
;             rs = rsqrtf(ssum * (g.dvshift == 9 ? (1.0f / 512.0f) : (1.0f / 256.0f)) + EPS); }
;           bf16_t* op = g.o0 + (size_t)row * N + col;
;           const u32x4 ow = gld<u32x4>(op);
;           const float ru = gld<float>(g.rowscale + row);
;           const f32x4 v0 = acc[ai][bj][m][0] * ru, v1 = acc[ai][bj][m][1] * ru;
;           float o[8] = {bflo(ow.x), bfhi(ow.x), bflo(ow.y), bfhi(ow.y), bflo(ow.z), bfhi(ow.z), bflo(ow.w), bfhi(ow.w)};
; #pragma unroll
;           for (int j = 0; j < 4; ++j) { o[j] = o[j] * rs * g0[j] * v0[j] * sigmoidf_(v0[j]); o[4 + j] = o[4 + j] * rs * g1[j] * v1[j] * sigmoidf_(v1[j]); }
;           u32x4 w; w.x = pk(o[0], o[1]); w.y = pk(o[2], o[3]); w.z = pk(o[4], o[5]); w.w = pk(o[6], o[7]);
;           gst<u32x4>(op, w);
	v_div_scale_f32 v136, vcc, v174, v174, 1.0
	v_rcp_f32_e32 v138, v136
	s_nop 0
	v_fma_f32 v167, -v136, v138, 1.0
	v_fmac_f32_e32 v138, v167, v138
	v_div_scale_f32 v167, vcc, 1.0, v174, 1.0
	v_mul_f32_e32 v169, v167, v138
	v_fma_f32 v176, -v136, v169, v167
	v_fmac_f32_e32 v169, v176, v138
	v_fma_f32 v136, -v136, v169, v167
	v_div_fmas_f32 v136, v136, v138, v169
	v_pk_mul_f32 v[176:177], v[126:127], v[168:169] op_sel_hi:[1,0]
	v_div_fixup_f32 v174, v136, v174, 1.0
	v_mul_f32_e32 v138, 0xbfb8aa3b, v176
	v_pk_mul_f32 v[172:173], v[174:175], v[172:173]
	v_exp_f32_e32 v174, v138
	v_mul_f32_e32 v138, 0xbfb8aa3b, v177
	v_exp_f32_e32 v175, v138
	v_lshlrev_b32_e32 v136, 16, v137
	v_and_b32_e32 v137, 0xffff0000, v137
	v_pk_mul_f32 v[136:137], v[148:149], v[136:137] op_sel_hi:[0,1]
	v_pk_add_f32 v[174:175], v[174:175], 1.0 op_sel_hi:[1,0]
	v_pk_mul_f32 v[136:137], v[134:135], v[136:137]
	v_div_scale_f32 v138, vcc, v175, v175, 1.0
	v_rcp_f32_e32 v167, v138
	v_pk_mul_f32 v[136:137], v[176:177], v[136:137]
	v_fma_f32 v169, -v138, v167, 1.0
	v_fmac_f32_e32 v167, v169, v167
	v_div_scale_f32 v169, vcc, 1.0, v175, 1.0
	v_mul_f32_e32 v176, v169, v167
	v_fma_f32 v177, -v138, v176, v169
	v_fmac_f32_e32 v176, v177, v167
	v_fma_f32 v138, -v138, v176, v169
	v_div_fmas_f32 v138, v138, v167, v176
	v_div_fixup_f32 v175, v138, v175, 1.0
	v_div_scale_f32 v138, vcc, v174, v174, 1.0
	v_rcp_f32_e32 v167, v138
	s_nop 0
	v_fma_f32 v169, -v138, v167, 1.0
	v_fmac_f32_e32 v167, v169, v167
	v_div_scale_f32 v169, vcc, 1.0, v174, 1.0
	v_mul_f32_e32 v176, v169, v167
	v_fma_f32 v177, -v138, v176, v169
	v_fmac_f32_e32 v176, v177, v167
	v_fma_f32 v138, -v138, v176, v169
	v_div_fmas_f32 v138, v138, v167, v176
	v_div_fixup_f32 v174, v138, v174, 1.0
	v_pk_mul_f32 v[174:175], v[174:175], v[136:137]
	v_lshlrev_b32_e32 v136, 16, v139
	v_and_b32_e32 v137, 0xffff0000, v139
	v_pk_mul_f32 v[136:137], v[148:149], v[136:137] op_sel_hi:[0,1]
	v_pk_mul_f32 v[138:139], v[122:123], v[168:169] op_sel_hi:[1,0]
	v_pk_mul_f32 v[136:137], v[130:131], v[136:137]
	v_mul_f32_e32 v167, 0xbfb8aa3b, v138
	v_pk_mul_f32 v[136:137], v[138:139], v[136:137]
	v_mul_f32_e32 v138, 0xbfb8aa3b, v139
	v_exp_f32_e32 v168, v167
	v_exp_f32_e32 v169, v138
	s_nop 0
	v_pk_add_f32 v[138:139], v[168:169], 1.0 op_sel_hi:[1,0]
	s_nop 0
	v_div_scale_f32 v148, vcc, v139, v139, 1.0
	v_rcp_f32_e32 v167, v148
	s_nop 0
	v_fma_f32 v168, -v148, v167, 1.0
	v_fmac_f32_e32 v167, v168, v167
	v_div_scale_f32 v168, vcc, 1.0, v139, 1.0
	v_mul_f32_e32 v169, v168, v167
	v_fma_f32 v176, -v148, v169, v168
	v_fmac_f32_e32 v169, v176, v167
	v_fma_f32 v148, -v148, v169, v168
	v_div_fmas_f32 v148, v148, v167, v169
	v_div_fixup_f32 v139, v148, v139, 1.0
	v_div_scale_f32 v148, vcc, v138, v138, 1.0
	v_rcp_f32_e32 v167, v148
	s_nop 0
	v_fma_f32 v168, -v148, v167, 1.0
	v_fmac_f32_e32 v167, v168, v167
	v_div_scale_f32 v168, vcc, 1.0, v138, 1.0
	v_mul_f32_e32 v169, v168, v167
	v_fma_f32 v176, -v148, v169, v168
	v_fmac_f32_e32 v169, v176, v167
	v_fma_f32 v148, -v148, v169, v168
	v_div_fmas_f32 v148, v148, v167, v169
	v_div_fixup_f32 v138, v148, v138, 1.0
	v_pk_mul_f32 v[168:169], v[138:139], v[136:137]
	v_cvt_pk_bf16_f32 v136, v170, v171
	v_cvt_pk_bf16_f32 v137, v174, v175
	v_cvt_pk_bf16_f32 v138, v172, v173
	v_cvt_pk_bf16_f32 v139, v168, v169
	global_store_dwordx4 v[142:143], v[136:139], off
	s_and_b64 vcc, exec, s[44:45]
	s_nop 0
	v_or_b32_e32 v136, 16, v166
	v_ashrrev_i32_e32 v137, 31, v136
	v_lshlrev_b64 v[138:139], 7, v[136:137]
	v_lshl_add_u64 v[184:185], s[66:67], 0, v[138:139]
	v_lshl_add_u64 v[168:169], v[180:181], 2, v[184:185]
	global_load_dwordx4 v[170:173], v[168:169], off
	global_load_dwordx4 v[232:235], v[168:169], off offset:16
	v_mad_u64_u32 v[238:239], s[100:101], v136, s70, 0
	v_mov_b32_e32 v240, v239
	v_mad_u64_u32 v[240:241], s[100:101], v137, s70, v[240:241]
	v_mov_b32_e32 v239, v240
	v_lshl_add_u64 v[238:239], v[238:239], 1, s[64:65]
	v_lshl_add_u64 v[236:237], v[164:165], 1, v[238:239]
	global_load_dwordx4 v[242:245], v[236:237], off
	global_load_dword v246, v[140:141], off offset:64
	s_waitcnt vmcnt(0)
	v_mov_b32_e32 v138, v171
	v_mov_b32_e32 v139, v172
	v_mov_b32_e32 v171, v173
	v_pk_add_f32 v[138:139], v[138:139], v[170:171]
	s_nop 0
	v_pk_add_f32 v[138:139], v[138:139], v[138:139] op_sel:[0,1] op_sel_hi:[1,0]
	s_cbranch_vccnz .LBB0_223
	v_mov_b64_e32 v[168:169], v[232:233]
	v_mov_b64_e32 v[170:171], v[234:235]
	s_mov_b32 s26, 0x3b000000
	v_mov_b32_e32 v172, v169
	v_mov_b32_e32 v173, v170
	v_mov_b32_e32 v169, v171
	v_pk_add_f32 v[168:169], v[172:173], v[168:169]
	s_nop 0
	v_add_f32_e32 v139, v168, v169
	v_add_f32_e32 v138, v138, v139
